# MLA: cross-half row-max exchange moved into the rare rescale path (the any-lane threshold test needs only per-lane maxima)
# baseline (speedup 1.0000x reference)
; __device__ __forceinline__ float ex2(float x) { return __builtin_amdgcn_exp2f(x); }
; template <bool MASK> __device__ __forceinline__ void sm_tile(f32x16& p0, f32x16& p1, float& mrun, float& lrun, f32x16& o0, f32x16& o1, LAS float* wsf, int kv0, int qpos, int q32, int hi) {
;     ...
;     float rm = fmaxf(p0[0], p1[0]);
; #pragma unroll
;     for (int r = 1; r < 16; ++r) rm = fmaxf(rm, fmaxf(p0[r], p1[r]));
;     rm = fmaxf(rm, xhalf(rm, hi));
;     if (__any(rm > mrun + 8.0f)) {
;         const float mnew = fmaxf(mrun, rm), alpha = ex2(mrun - mnew); mrun = mnew; lrun *= alpha;
.LBB0_48:
	v_lshl_add_u64 v[2:3], s[22:23], 0, v[166:167]
	v_add_co_u32_e32 v4, vcc, 0x104a0000, v2
	v_lshl_add_u64 v[10:11], s[22:23], 0, v[162:163]
	s_nop 0
	v_addc_co_u32_e32 v5, vcc, 0, v3, vcc
	v_add_co_u32_e32 v2, vcc, 0x104c0000, v2
	s_and_b32 s43, s19, 1
	s_nop 0
	v_addc_co_u32_e32 v3, vcc, 0, v3, vcc
	v_add_co_u32_e32 v14, vcc, 0x12460000, v10
	global_load_dwordx4 v[6:9], v[4:5], off
	s_nop 0
	global_load_dwordx4 v[2:5], v[2:3], off
	v_addc_co_u32_e32 v15, vcc, 0, v11, vcc
	global_load_dwordx4 v[10:13], v[14:15], off offset:256
	global_load_dwordx4 v[108:111], v[14:15], off offset:384
	v_lshl_add_u64 v[14:15], s[22:23], 0, v[164:165]
	global_load_dwordx4 v[112:115], v[14:15], off
	s_mul_i32 s20, s43, 0x6800
	v_add_u32_e32 v1, s20, v175
	s_mul_i32 s20, s43, 0x4200
	v_add_u32_e32 v15, s20, v174
	v_add_u32_e32 v14, 0xd000, v15
	v_add_u32_e32 v176, 0xf000, v15
	ds_read_b128 v[116:119], v1 offset:0
	ds_read_b128 v[120:123], v1 offset:32
	ds_read_b128 v[124:127], v1 offset:64
	ds_read_b128 v[128:131], v1 offset:96
	ds_read_b128 v[132:135], v1 offset:128
	ds_read_b128 v[136:139], v1 offset:160
	s_waitcnt lgkmcnt(5)
	v_mfma_f32_32x32x16_bf16 v[64:79], v[116:119], v[84:87], v[198:213]
	s_waitcnt lgkmcnt(4)
	v_mfma_f32_32x32x16_bf16 v[64:79], v[120:123], v[88:91], v[64:79]
	s_waitcnt lgkmcnt(3)
	v_mfma_f32_32x32x16_bf16 v[64:79], v[124:127], v[92:95], v[64:79]
	s_waitcnt lgkmcnt(2)
	v_mfma_f32_32x32x16_bf16 v[64:79], v[128:131], v[96:99], v[64:79]
	s_waitcnt lgkmcnt(1)
	v_mfma_f32_32x32x16_bf16 v[64:79], v[132:135], v[100:103], v[64:79]
	s_waitcnt lgkmcnt(0)
	v_mfma_f32_32x32x16_bf16 v[64:79], v[136:139], v[104:107], v[64:79]
	s_waitcnt lgkmcnt(0)
	ds_read_b128 v[116:119], v1 offset:6656
	ds_read_b128 v[120:123], v1 offset:6688
	ds_read_b128 v[124:127], v1 offset:6720
	ds_read_b128 v[128:131], v1 offset:6752
	ds_read_b128 v[132:135], v1 offset:6784
	ds_read_b128 v[136:139], v1 offset:6816
	ds_read2_b64 v[140:143], v14 offset0:0 offset1:2
	ds_read2_b64 v[144:147], v176 offset0:32 offset1:34
	ds_read2_b64 v[180:183], v14 offset0:4 offset1:6
	ds_read2_b64 v[184:187], v176 offset0:36 offset1:38
	s_nop 1
	v_max3_f32 v15, v64, v65, v66
	v_max3_f32 v177, v67, v68, v69
	v_max3_f32 v15, v15, v70, v71
	v_max3_f32 v177, v177, v72, v73
	v_max3_f32 v15, v15, v74, v75
	v_max3_f32 v177, v177, v76, v77
	v_max3_f32 v15, v15, v78, v79
	v_max_f32_e32 v15, v15, v177
	v_cmp_gt_f32_e32 vcc, v15, v197
	s_cbranch_vccz .Lm3_ok1
	v_mov_b32_e32 v177, v15
	v_mov_b32_e32 v178, v15
	s_nop 1
	v_permlane32_swap_b32_e32 v177, v178
	v_max3_f32 v15, v15, v177, v178
	v_max_f32_e32 v15, v171, v15
	v_sub_f32_e32 v177, v171, v15
	v_exp_f32_e32 v177, v177
	v_sub_f32_e32 v198, v198, v15
	s_and_saveexec_b64 s[20:21], s[40:41]
	ds_write_b32 v149, v177
	s_or_b64 exec, exec, s[20:21]
	v_mul_f32_e32 v170, v170, v177
	v_add_u32_e32 v178, s25, v148
	s_waitcnt lgkmcnt(0)
	ds_read_b128 v[188:191], v178
	ds_read_b128 v[192:195], v178 offset:32
	ds_read_b128 v[222:225], v178 offset:64
	ds_read_b128 v[236:239], v178 offset:96
	v_sub_f32_e32 v64, v64, v15
	v_sub_f32_e32 v65, v65, v15
	v_sub_f32_e32 v66, v66, v15
	v_sub_f32_e32 v67, v67, v15
	v_sub_f32_e32 v68, v68, v15
	v_sub_f32_e32 v69, v69, v15
	v_sub_f32_e32 v70, v70, v15
	v_sub_f32_e32 v71, v71, v15
	v_sub_f32_e32 v72, v72, v15
	v_sub_f32_e32 v73, v73, v15
	v_sub_f32_e32 v74, v74, v15
	v_sub_f32_e32 v75, v75, v15
	v_sub_f32_e32 v76, v76, v15
	v_sub_f32_e32 v77, v77, v15
	v_sub_f32_e32 v78, v78, v15
	v_sub_f32_e32 v79, v79, v15
	v_mov_b32_e32 v199, v198
	v_mov_b32_e32 v200, v198
	v_mov_b32_e32 v201, v198
	v_mov_b32_e32 v202, v198
	v_mov_b32_e32 v203, v198
	v_mov_b32_e32 v204, v198
	v_mov_b32_e32 v205, v198
	v_mov_b32_e32 v206, v198
	v_mov_b32_e32 v207, v198
	v_mov_b32_e32 v208, v198
	v_mov_b32_e32 v209, v198
	v_mov_b32_e32 v210, v198
	v_mov_b32_e32 v211, v198
	v_mov_b32_e32 v212, v198
	v_mov_b32_e32 v213, v198
	v_mov_b32_e32 v171, 0
	v_mov_b32_e32 v197, 0x41000000
	s_nop 11
	s_nop 3
	s_waitcnt lgkmcnt(0)
	v_pk_mul_f32 v[16:17], v[16:17], v[188:189]
	v_pk_mul_f32 v[32:33], v[32:33], v[188:189]
	v_pk_mul_f32 v[18:19], v[18:19], v[190:191]
	v_pk_mul_f32 v[34:35], v[34:35], v[190:191]
	v_pk_mul_f32 v[20:21], v[20:21], v[192:193]
	v_pk_mul_f32 v[36:37], v[36:37], v[192:193]
	v_pk_mul_f32 v[22:23], v[22:23], v[194:195]
	v_pk_mul_f32 v[38:39], v[38:39], v[194:195]
	v_pk_mul_f32 v[24:25], v[24:25], v[222:223]
	v_pk_mul_f32 v[40:41], v[40:41], v[222:223]
	v_pk_mul_f32 v[26:27], v[26:27], v[224:225]
	v_pk_mul_f32 v[42:43], v[42:43], v[224:225]
	v_pk_mul_f32 v[28:29], v[28:29], v[236:237]
	v_pk_mul_f32 v[44:45], v[44:45], v[236:237]
	v_pk_mul_f32 v[30:31], v[30:31], v[238:239]
	v_pk_mul_f32 v[46:47], v[46:47], v[238:239]
; template <bool MASK> __device__ __forceinline__ void sm_tile(f32x16& p0, f32x16& p1, float& mrun, float& lrun, f32x16& o0, f32x16& o1, LAS float* wsf, int kv0, int qpos, int q32, int hi) {
;     ...
;     float rm = fmaxf(p0[0], p1[0]);
; #pragma unroll
;     for (int r = 1; r < 16; ++r) rm = fmaxf(rm, fmaxf(p0[r], p1[r]));
;     rm = fmaxf(rm, xhalf(rm, hi));
;     if (__any(rm > mrun + 8.0f)) {
;         const float mnew = fmaxf(mrun, rm), alpha = ex2(mrun - mnew); mrun = mnew; lrun *= alpha;
;         if (hi == 0) wsf[q32] = alpha;
; template <bool MASK> __device__ __forceinline__ void sm_iter(int var, SmState& st, const bf16x8 (&qr)[6], const LAS unsigned char* kb, const LAS unsigned char* vb, LAS float* wsf, int kv0, int qpos, int q32, int hi) {
;     ...
;     for (int d0 = 0; d0 < ND; ++d0) { kf[2 * d0] = *(const LAS bf16x8*)(kb + d0 * 32); kf[2 * d0 + 1] = *(const LAS bf16x8*)(kb + 32 * KP + d0 * 32); }
;     __builtin_amdgcn_sched_barrier(0);
; #pragma unroll
;     for (int d0 = 0; d0 < ND; ++d0) { p0 = MFMA32(kf[2 * d0], qr[d0], p0); p1 = MFMA32(kf[2 * d0 + 1], qr[d0], p1); }
; #pragma unroll
;     for (int j = 0; j < 4; ++j) { vlo[2 * j] = *(const LAS s16x4*)(vb + j * 32); vhh[2 * j] = *(const LAS s16x4*)(vb + j * 32 + 16);
;         vlo[2 * j + 1] = *(const LAS s16x4*)(vb + 32 * VP + j * 32); vhh[2 * j + 1] = *(const LAS s16x4*)(vb + 32 * VP + j * 32 + 16); }
;     __builtin_amdgcn_sched_barrier(0);
;     if (var != 1) sm_tile<MASK>(p0, p1, st.mrun, st.lrun, st.o0, st.o1, wsf, kv0, qpos, q32, hi);
; #pragma unroll
;     for (int j = 0; j < 4; ++j) {
;         u32x4 pw;
;         if (j < 2) { const int r0 = 8 * (j & 1); pw.x = pk2(p0[r0], p0[r0 + 1]); pw.y = pk2(p0[r0 + 2], p0[r0 + 3]); pw.z = pk2(p0[r0 + 4], p0[r0 + 5]); pw.w = pk2(p0[r0 + 6], p0[r0 + 7]); }
;         else { const int r0 = 8 * (j & 1); pw.x = pk2(p1[r0], p1[r0 + 1]); pw.y = pk2(p1[r0 + 2], p1[r0 + 3]); pw.z = pk2(p1[r0 + 4], p1[r0 + 5]); pw.w = pk2(p1[r0 + 6], p1[r0 + 7]); }
;         const bf16x8 pa = __builtin_bit_cast(bf16x8, pw);
;         { const s16x4 lo = vlo[2 * j], hh = vhh[2 * j]; const bf16x8 vf = {lo[0], lo[1], lo[2], lo[3], hh[0], hh[1], hh[2], hh[3]}; st.o0 = MFMA32(pa, vf, st.o0); }
;         { const s16x4 lo = vlo[2 * j + 1], hh = vhh[2 * j + 1]; const bf16x8 vf = {lo[0], lo[1], lo[2], lo[3], hh[0], hh[1], hh[2], hh[3]}; st.o1 = MFMA32(pa, vf, st.o1); }
.Lm3_ok1:
.Lm3_body:
	v_exp_f32_e32 v64, v64
	v_exp_f32_e32 v65, v65
	v_exp_f32_e32 v66, v66
	s_waitcnt lgkmcnt(9)
	v_mfma_f32_32x32x16_bf16 v[48:63], v[116:119], v[84:87], v[198:213]
	v_add_f32_e32 v15, v64, v65
	v_exp_f32_e32 v67, v67
	v_cvt_pk_bf16_f32 v214, v64, v65
	v_exp_f32_e32 v68, v68
	v_add_f32_e32 v177, v66, v67
	v_exp_f32_e32 v69, v69
	v_cvt_pk_bf16_f32 v215, v66, v67
	s_waitcnt lgkmcnt(8)
	v_mfma_f32_32x32x16_bf16 v[48:63], v[120:123], v[88:91], v[48:63]
	v_exp_f32_e32 v70, v70
	v_add_f32_e32 v15, v15, v68
	v_exp_f32_e32 v71, v71
	v_add_f32_e32 v177, v177, v69
	v_exp_f32_e32 v72, v72
	v_cvt_pk_bf16_f32 v216, v68, v69
	s_waitcnt lgkmcnt(7)
	v_mfma_f32_32x32x16_bf16 v[48:63], v[124:127], v[92:95], v[48:63]
	v_exp_f32_e32 v73, v73
	v_add_f32_e32 v15, v15, v70
	v_exp_f32_e32 v74, v74
	v_add_f32_e32 v177, v177, v71
	v_exp_f32_e32 v75, v75
	v_cvt_pk_bf16_f32 v217, v70, v71
	s_waitcnt lgkmcnt(6)
	v_mfma_f32_32x32x16_bf16 v[48:63], v[128:131], v[96:99], v[48:63]
	v_exp_f32_e32 v76, v76
	v_add_f32_e32 v15, v15, v72
	v_exp_f32_e32 v77, v77
	v_add_f32_e32 v177, v177, v73
	v_exp_f32_e32 v78, v78
	v_cvt_pk_bf16_f32 v218, v72, v73
	s_waitcnt lgkmcnt(5)
	v_mfma_f32_32x32x16_bf16 v[48:63], v[132:135], v[100:103], v[48:63]
	v_exp_f32_e32 v79, v79
	v_add_f32_e32 v15, v15, v74
	v_add_f32_e32 v177, v177, v75
	v_cvt_pk_bf16_f32 v219, v74, v75
	v_add_f32_e32 v15, v15, v76
	v_add_f32_e32 v177, v177, v77
	s_waitcnt lgkmcnt(4)
	v_mfma_f32_32x32x16_bf16 v[48:63], v[136:139], v[104:107], v[48:63]
	v_cvt_pk_bf16_f32 v220, v76, v77
	v_add_f32_e32 v15, v15, v78
	v_add_f32_e32 v177, v177, v79
	v_cvt_pk_bf16_f32 v221, v78, v79
	v_add_f32_e32 v15, v15, v177
	v_add_f32_e32 v170, v170, v15
	s_waitcnt lgkmcnt(0)
	ds_read_b128 v[116:119], v1 offset:13312
	ds_read_b128 v[120:123], v1 offset:13344
	ds_read_b128 v[124:127], v1 offset:13376
	ds_read_b128 v[128:131], v1 offset:13408
	ds_read_b128 v[132:135], v1 offset:13440
	ds_read_b128 v[136:139], v1 offset:13472
	v_mfma_f32_32x32x16_bf16 v[16:31], v[214:217], v[140:143], v[16:31]
	ds_read2_b64 v[140:143], v14 offset0:8 offset1:10
	v_mfma_f32_32x32x16_bf16 v[32:47], v[214:217], v[144:147], v[32:47]
	ds_read2_b64 v[144:147], v176 offset0:40 offset1:42
	v_mfma_f32_32x32x16_bf16 v[16:31], v[218:221], v[180:183], v[16:31]
	ds_read2_b64 v[180:183], v14 offset0:12 offset1:14
	v_mfma_f32_32x32x16_bf16 v[32:47], v[218:221], v[184:187], v[32:47]
	ds_read2_b64 v[184:187], v176 offset0:44 offset1:46
	v_max3_f32 v15, v48, v49, v50
	v_max3_f32 v177, v51, v52, v53
	v_max3_f32 v15, v15, v54, v55
	v_max3_f32 v177, v177, v56, v57
	v_max3_f32 v15, v15, v58, v59
	v_max3_f32 v177, v177, v60, v61
	v_max3_f32 v15, v15, v62, v63
	v_max_f32_e32 v15, v15, v177
	v_cmp_gt_f32_e32 vcc, v15, v197
	s_cbranch_vccz .Lm3_ok2
	v_mov_b32_e32 v177, v15
	v_mov_b32_e32 v178, v15
	s_nop 1
	v_permlane32_swap_b32_e32 v177, v178
	v_max3_f32 v15, v15, v177, v178
	v_max_f32_e32 v15, v171, v15
	v_sub_f32_e32 v177, v171, v15
	v_exp_f32_e32 v177, v177
	v_sub_f32_e32 v198, v198, v15
	s_and_saveexec_b64 s[20:21], s[40:41]
	ds_write_b32 v149, v177
	s_or_b64 exec, exec, s[20:21]
	v_mul_f32_e32 v170, v170, v177
	v_add_u32_e32 v178, s25, v148
	s_waitcnt lgkmcnt(0)
	ds_read_b128 v[188:191], v178
	ds_read_b128 v[192:195], v178 offset:32
	ds_read_b128 v[222:225], v178 offset:64
	ds_read_b128 v[236:239], v178 offset:96
	v_sub_f32_e32 v48, v48, v15
	v_sub_f32_e32 v49, v49, v15
	v_sub_f32_e32 v50, v50, v15
	v_sub_f32_e32 v51, v51, v15
	v_sub_f32_e32 v52, v52, v15
	v_sub_f32_e32 v53, v53, v15
	v_sub_f32_e32 v54, v54, v15
	v_sub_f32_e32 v55, v55, v15
	v_sub_f32_e32 v56, v56, v15
	v_sub_f32_e32 v57, v57, v15
	v_sub_f32_e32 v58, v58, v15
	v_sub_f32_e32 v59, v59, v15
	v_sub_f32_e32 v60, v60, v15
	v_sub_f32_e32 v61, v61, v15
	v_sub_f32_e32 v62, v62, v15
	v_sub_f32_e32 v63, v63, v15
	v_mov_b32_e32 v199, v198
	v_mov_b32_e32 v200, v198
	v_mov_b32_e32 v201, v198
	v_mov_b32_e32 v202, v198
	v_mov_b32_e32 v203, v198
	v_mov_b32_e32 v204, v198
	v_mov_b32_e32 v205, v198
	v_mov_b32_e32 v206, v198
	v_mov_b32_e32 v207, v198
	v_mov_b32_e32 v208, v198
	v_mov_b32_e32 v209, v198
	v_mov_b32_e32 v210, v198
	v_mov_b32_e32 v211, v198
	v_mov_b32_e32 v212, v198
	v_mov_b32_e32 v213, v198
	v_mov_b32_e32 v171, 0
	v_mov_b32_e32 v197, 0x41000000
	s_nop 11
	s_nop 3
	s_waitcnt lgkmcnt(0)
	v_pk_mul_f32 v[16:17], v[16:17], v[188:189]
	v_pk_mul_f32 v[32:33], v[32:33], v[188:189]
	v_pk_mul_f32 v[18:19], v[18:19], v[190:191]
	v_pk_mul_f32 v[34:35], v[34:35], v[190:191]
	v_pk_mul_f32 v[20:21], v[20:21], v[192:193]
	v_pk_mul_f32 v[36:37], v[36:37], v[192:193]
	v_pk_mul_f32 v[22:23], v[22:23], v[194:195]
	v_pk_mul_f32 v[38:39], v[38:39], v[194:195]
	v_pk_mul_f32 v[24:25], v[24:25], v[222:223]
	v_pk_mul_f32 v[40:41], v[40:41], v[222:223]
	v_pk_mul_f32 v[26:27], v[26:27], v[224:225]
	v_pk_mul_f32 v[42:43], v[42:43], v[224:225]
	v_pk_mul_f32 v[28:29], v[28:29], v[236:237]
	v_pk_mul_f32 v[44:45], v[44:45], v[236:237]
	v_pk_mul_f32 v[30:31], v[30:31], v[238:239]
	v_pk_mul_f32 v[46:47], v[46:47], v[238:239]
; template <bool MASK> __device__ __forceinline__ void sm_tile(f32x16& p0, f32x16& p1, float& mrun, float& lrun, f32x16& o0, f32x16& o1, LAS float* wsf, int kv0, int qpos, int q32, int hi) {
;     ...
;     float rm = fmaxf(p0[0], p1[0]);
; #pragma unroll
;     for (int r = 1; r < 16; ++r) rm = fmaxf(rm, fmaxf(p0[r], p1[r]));
;     rm = fmaxf(rm, xhalf(rm, hi));
;     if (__any(rm > mrun + 8.0f)) {
;         const float mnew = fmaxf(mrun, rm), alpha = ex2(mrun - mnew); mrun = mnew; lrun *= alpha;
;         if (hi == 0) wsf[q32] = alpha;
; template <bool MASK> __device__ __forceinline__ void sm_iter(int var, SmState& st, const bf16x8 (&qr)[6], const LAS unsigned char* kb, const LAS unsigned char* vb, LAS float* wsf, int kv0, int qpos, int q32, int hi) {
;     ...
;     for (int d0 = 0; d0 < ND; ++d0) { kf[2 * d0] = *(const LAS bf16x8*)(kb + d0 * 32); kf[2 * d0 + 1] = *(const LAS bf16x8*)(kb + 32 * KP + d0 * 32); }
;     __builtin_amdgcn_sched_barrier(0);
; #pragma unroll
;     for (int d0 = 0; d0 < ND; ++d0) { p0 = MFMA32(kf[2 * d0], qr[d0], p0); p1 = MFMA32(kf[2 * d0 + 1], qr[d0], p1); }
; #pragma unroll
;     for (int j = 0; j < 4; ++j) { vlo[2 * j] = *(const LAS s16x4*)(vb + j * 32); vhh[2 * j] = *(const LAS s16x4*)(vb + j * 32 + 16);
;         vlo[2 * j + 1] = *(const LAS s16x4*)(vb + 32 * VP + j * 32); vhh[2 * j + 1] = *(const LAS s16x4*)(vb + 32 * VP + j * 32 + 16); }
;     __builtin_amdgcn_sched_barrier(0);
;     if (var != 1) sm_tile<MASK>(p0, p1, st.mrun, st.lrun, st.o0, st.o1, wsf, kv0, qpos, q32, hi);
; #pragma unroll
;     for (int j = 0; j < 4; ++j) {
;         u32x4 pw;
;         if (j < 2) { const int r0 = 8 * (j & 1); pw.x = pk2(p0[r0], p0[r0 + 1]); pw.y = pk2(p0[r0 + 2], p0[r0 + 3]); pw.z = pk2(p0[r0 + 4], p0[r0 + 5]); pw.w = pk2(p0[r0 + 6], p0[r0 + 7]); }
;         else { const int r0 = 8 * (j & 1); pw.x = pk2(p1[r0], p1[r0 + 1]); pw.y = pk2(p1[r0 + 2], p1[r0 + 3]); pw.z = pk2(p1[r0 + 4], p1[r0 + 5]); pw.w = pk2(p1[r0 + 6], p1[r0 + 7]); }
;         const bf16x8 pa = __builtin_bit_cast(bf16x8, pw);
;         { const s16x4 lo = vlo[2 * j], hh = vhh[2 * j]; const bf16x8 vf = {lo[0], lo[1], lo[2], lo[3], hh[0], hh[1], hh[2], hh[3]}; st.o0 = MFMA32(pa, vf, st.o0); }
;         { const s16x4 lo = vlo[2 * j + 1], hh = vhh[2 * j + 1]; const bf16x8 vf = {lo[0], lo[1], lo[2], lo[3], hh[0], hh[1], hh[2], hh[3]}; st.o1 = MFMA32(pa, vf, st.o1); }
.Lm3_ok2:
	v_exp_f32_e32 v48, v48
	v_exp_f32_e32 v49, v49
	v_exp_f32_e32 v50, v50
	s_waitcnt lgkmcnt(9)
	v_mfma_f32_32x32x16_bf16 v[64:79], v[116:119], v[84:87], v[198:213]
	v_add_f32_e32 v15, v48, v49
	v_exp_f32_e32 v51, v51
	v_cvt_pk_bf16_f32 v214, v48, v49
	v_exp_f32_e32 v52, v52
	v_add_f32_e32 v177, v50, v51
	v_exp_f32_e32 v53, v53
	v_cvt_pk_bf16_f32 v215, v50, v51
	s_waitcnt lgkmcnt(8)
	v_mfma_f32_32x32x16_bf16 v[64:79], v[120:123], v[88:91], v[64:79]
	v_exp_f32_e32 v54, v54
	v_add_f32_e32 v15, v15, v52
	v_exp_f32_e32 v55, v55
	v_add_f32_e32 v177, v177, v53
	v_exp_f32_e32 v56, v56
	v_cvt_pk_bf16_f32 v216, v52, v53
	s_waitcnt lgkmcnt(7)
	v_mfma_f32_32x32x16_bf16 v[64:79], v[124:127], v[92:95], v[64:79]
	v_exp_f32_e32 v57, v57
	v_add_f32_e32 v15, v15, v54
	v_exp_f32_e32 v58, v58
	v_add_f32_e32 v177, v177, v55
	v_exp_f32_e32 v59, v59
	v_cvt_pk_bf16_f32 v217, v54, v55
	s_waitcnt lgkmcnt(6)
	v_mfma_f32_32x32x16_bf16 v[64:79], v[128:131], v[96:99], v[64:79]
	v_exp_f32_e32 v60, v60
	v_add_f32_e32 v15, v15, v56
	v_exp_f32_e32 v61, v61
	v_add_f32_e32 v177, v177, v57
	v_exp_f32_e32 v62, v62
	v_cvt_pk_bf16_f32 v218, v56, v57
	s_waitcnt lgkmcnt(5)
	v_mfma_f32_32x32x16_bf16 v[64:79], v[132:135], v[100:103], v[64:79]
	v_exp_f32_e32 v63, v63
	v_add_f32_e32 v15, v15, v58
	v_add_f32_e32 v177, v177, v59
	v_cvt_pk_bf16_f32 v219, v58, v59
	v_add_f32_e32 v15, v15, v60
	v_add_f32_e32 v177, v177, v61
	s_waitcnt lgkmcnt(4)
	v_mfma_f32_32x32x16_bf16 v[64:79], v[136:139], v[104:107], v[64:79]
	v_cvt_pk_bf16_f32 v220, v60, v61
	v_add_f32_e32 v15, v15, v62
	v_add_f32_e32 v177, v177, v63
	v_cvt_pk_bf16_f32 v221, v62, v63
	v_add_f32_e32 v15, v15, v177
	v_add_f32_e32 v170, v170, v15
	s_waitcnt lgkmcnt(0)
	ds_read_b128 v[116:119], v1 offset:19968
	ds_read_b128 v[120:123], v1 offset:20000
	ds_read_b128 v[124:127], v1 offset:20032
	ds_read_b128 v[128:131], v1 offset:20064
	ds_read_b128 v[132:135], v1 offset:20096
	ds_read_b128 v[136:139], v1 offset:20128
	v_mfma_f32_32x32x16_bf16 v[16:31], v[214:217], v[140:143], v[16:31]
	ds_read2_b64 v[140:143], v14 offset0:16 offset1:18
	v_mfma_f32_32x32x16_bf16 v[32:47], v[214:217], v[144:147], v[32:47]
	ds_read2_b64 v[144:147], v176 offset0:48 offset1:50
	v_mfma_f32_32x32x16_bf16 v[16:31], v[218:221], v[180:183], v[16:31]
	ds_read2_b64 v[180:183], v14 offset0:20 offset1:22
	v_mfma_f32_32x32x16_bf16 v[32:47], v[218:221], v[184:187], v[32:47]
	ds_read2_b64 v[184:187], v176 offset0:52 offset1:54
	v_max3_f32 v15, v64, v65, v66
	v_max3_f32 v177, v67, v68, v69
	v_max3_f32 v15, v15, v70, v71
	v_max3_f32 v177, v177, v72, v73
	v_max3_f32 v15, v15, v74, v75
	v_max3_f32 v177, v177, v76, v77
	v_max3_f32 v15, v15, v78, v79
	v_max_f32_e32 v15, v15, v177
	v_cmp_gt_f32_e32 vcc, v15, v197
	s_cbranch_vccz .Lm3_ok3
	v_mov_b32_e32 v177, v15
	v_mov_b32_e32 v178, v15
	s_nop 1
	v_permlane32_swap_b32_e32 v177, v178
	v_max3_f32 v15, v15, v177, v178
	v_max_f32_e32 v15, v171, v15
	v_sub_f32_e32 v177, v171, v15
	v_exp_f32_e32 v177, v177
	v_sub_f32_e32 v198, v198, v15
	s_and_saveexec_b64 s[20:21], s[40:41]
	ds_write_b32 v149, v177
	s_or_b64 exec, exec, s[20:21]
	v_mul_f32_e32 v170, v170, v177
	v_add_u32_e32 v178, s25, v148
	s_waitcnt lgkmcnt(0)
	ds_read_b128 v[188:191], v178
	ds_read_b128 v[192:195], v178 offset:32
	ds_read_b128 v[222:225], v178 offset:64
	ds_read_b128 v[236:239], v178 offset:96
	v_sub_f32_e32 v64, v64, v15
	v_sub_f32_e32 v65, v65, v15
	v_sub_f32_e32 v66, v66, v15
	v_sub_f32_e32 v67, v67, v15
	v_sub_f32_e32 v68, v68, v15
	v_sub_f32_e32 v69, v69, v15
	v_sub_f32_e32 v70, v70, v15
	v_sub_f32_e32 v71, v71, v15
	v_sub_f32_e32 v72, v72, v15
	v_sub_f32_e32 v73, v73, v15
	v_sub_f32_e32 v74, v74, v15
	v_sub_f32_e32 v75, v75, v15
	v_sub_f32_e32 v76, v76, v15
	v_sub_f32_e32 v77, v77, v15
	v_sub_f32_e32 v78, v78, v15
	v_sub_f32_e32 v79, v79, v15
	v_mov_b32_e32 v199, v198
	v_mov_b32_e32 v200, v198
	v_mov_b32_e32 v201, v198
	v_mov_b32_e32 v202, v198
	v_mov_b32_e32 v203, v198
	v_mov_b32_e32 v204, v198
	v_mov_b32_e32 v205, v198
	v_mov_b32_e32 v206, v198
	v_mov_b32_e32 v207, v198
	v_mov_b32_e32 v208, v198
	v_mov_b32_e32 v209, v198
	v_mov_b32_e32 v210, v198
	v_mov_b32_e32 v211, v198
	v_mov_b32_e32 v212, v198
	v_mov_b32_e32 v213, v198
	v_mov_b32_e32 v171, 0
	v_mov_b32_e32 v197, 0x41000000
	s_nop 11
	s_nop 3
	s_waitcnt lgkmcnt(0)
	v_pk_mul_f32 v[16:17], v[16:17], v[188:189]
	v_pk_mul_f32 v[32:33], v[32:33], v[188:189]
	v_pk_mul_f32 v[18:19], v[18:19], v[190:191]
	v_pk_mul_f32 v[34:35], v[34:35], v[190:191]
	v_pk_mul_f32 v[20:21], v[20:21], v[192:193]
	v_pk_mul_f32 v[36:37], v[36:37], v[192:193]
	v_pk_mul_f32 v[22:23], v[22:23], v[194:195]
	v_pk_mul_f32 v[38:39], v[38:39], v[194:195]
	v_pk_mul_f32 v[24:25], v[24:25], v[222:223]
	v_pk_mul_f32 v[40:41], v[40:41], v[222:223]
	v_pk_mul_f32 v[26:27], v[26:27], v[224:225]
	v_pk_mul_f32 v[42:43], v[42:43], v[224:225]
	v_pk_mul_f32 v[28:29], v[28:29], v[236:237]
	v_pk_mul_f32 v[44:45], v[44:45], v[236:237]
	v_pk_mul_f32 v[30:31], v[30:31], v[238:239]
	v_pk_mul_f32 v[46:47], v[46:47], v[238:239]
; #define LAS __attribute__((address_space(3)))
; __device__ __forceinline__ unsigned pk2(float lo, float hi) { f32x2_t v = {lo, hi}; bf16x2_t b = __builtin_convertvector(v, bf16x2_t); return __builtin_bit_cast(unsigned, b); }
; #define MFMA32(a, b, c) __builtin_amdgcn_mfma_f32_32x32x16_bf16((a), (b), (c), 0, 0, 0)
; template <bool MASK> __device__ __forceinline__ void sm_iter(int var, SmState& st, const bf16x8 (&qr)[6], const LAS unsigned char* kb, const LAS unsigned char* vb, LAS float* wsf, int kv0, int qpos, int q32, int hi) {
;     ...
;     for (int d0 = 0; d0 < ND; ++d0) { kf[2 * d0] = *(const LAS bf16x8*)(kb + d0 * 32); kf[2 * d0 + 1] = *(const LAS bf16x8*)(kb + 32 * KP + d0 * 32); }
;     __builtin_amdgcn_sched_barrier(0);
; #pragma unroll
;     for (int d0 = 0; d0 < ND; ++d0) { p0 = MFMA32(kf[2 * d0], qr[d0], p0); p1 = MFMA32(kf[2 * d0 + 1], qr[d0], p1); }
; #pragma unroll
;     for (int j = 0; j < 4; ++j) { vlo[2 * j] = *(const LAS s16x4*)(vb + j * 32); vhh[2 * j] = *(const LAS s16x4*)(vb + j * 32 + 16);
;         vlo[2 * j + 1] = *(const LAS s16x4*)(vb + 32 * VP + j * 32); vhh[2 * j + 1] = *(const LAS s16x4*)(vb + 32 * VP + j * 32 + 16); }
;     __builtin_amdgcn_sched_barrier(0);
;     if (var != 1) sm_tile<MASK>(p0, p1, st.mrun, st.lrun, st.o0, st.o1, wsf, kv0, qpos, q32, hi);
; #pragma unroll
;     for (int j = 0; j < 4; ++j) {
;         u32x4 pw;
;         if (j < 2) { const int r0 = 8 * (j & 1); pw.x = pk2(p0[r0], p0[r0 + 1]); pw.y = pk2(p0[r0 + 2], p0[r0 + 3]); pw.z = pk2(p0[r0 + 4], p0[r0 + 5]); pw.w = pk2(p0[r0 + 6], p0[r0 + 7]); }
;         else { const int r0 = 8 * (j & 1); pw.x = pk2(p1[r0], p1[r0 + 1]); pw.y = pk2(p1[r0 + 2], p1[r0 + 3]); pw.z = pk2(p1[r0 + 4], p1[r0 + 5]); pw.w = pk2(p1[r0 + 6], p1[r0 + 7]); }
;         const bf16x8 pa = __builtin_bit_cast(bf16x8, pw);
;         { const s16x4 lo = vlo[2 * j], hh = vhh[2 * j]; const bf16x8 vf = {lo[0], lo[1], lo[2], lo[3], hh[0], hh[1], hh[2], hh[3]}; st.o0 = MFMA32(pa, vf, st.o0); }
;         { const s16x4 lo = vlo[2 * j + 1], hh = vhh[2 * j + 1]; const bf16x8 vf = {lo[0], lo[1], lo[2], lo[3], hh[0], hh[1], hh[2], hh[3]}; st.o1 = MFMA32(pa, vf, st.o1); }
.Lm3_ok3:
	s_xor_b32 s20, s43, 1
	s_mul_i32 s21, s20, 0x6800
	s_add_i32 s21, s21, 0
	s_mulk_i32 s20, 0x4200
	v_add_u32_e32 v226, s21, v150
	s_waitcnt vmcnt(4)
	ds_write_b128 v226, v[6:9]
	s_waitcnt vmcnt(3)
	ds_write_b128 v226, v[2:5] offset:13312
	v_add_u32_e32 v226, s21, v152
	s_waitcnt vmcnt(0)
	ds_write_b128 v226, v[112:115] offset:128
	v_add_u32_e32 v226, s20, v151
	v_add_u32_e32 v227, 0xd000, v226
	v_add_u32_e32 v226, 0xd080, v226
	ds_write2_b64 v227, v[10:11], v[12:13] offset1:1
	ds_write2_b64 v226, v[108:109], v[110:111] offset1:1
	v_exp_f32_e32 v64, v64
	v_exp_f32_e32 v65, v65
	v_exp_f32_e32 v66, v66
	s_waitcnt lgkmcnt(14)
	v_mfma_f32_32x32x16_bf16 v[48:63], v[116:119], v[84:87], v[198:213]
	v_add_f32_e32 v15, v64, v65
	v_exp_f32_e32 v67, v67
	v_cvt_pk_bf16_f32 v214, v64, v65
	v_exp_f32_e32 v68, v68
	v_add_f32_e32 v177, v66, v67
	v_exp_f32_e32 v69, v69
	v_cvt_pk_bf16_f32 v215, v66, v67
	s_waitcnt lgkmcnt(13)
	v_mfma_f32_32x32x16_bf16 v[48:63], v[120:123], v[88:91], v[48:63]
	v_exp_f32_e32 v70, v70
	v_add_f32_e32 v15, v15, v68
	v_exp_f32_e32 v71, v71
	v_add_f32_e32 v177, v177, v69
	v_exp_f32_e32 v72, v72
	v_cvt_pk_bf16_f32 v216, v68, v69
	s_waitcnt lgkmcnt(12)
	v_mfma_f32_32x32x16_bf16 v[48:63], v[124:127], v[92:95], v[48:63]
	v_exp_f32_e32 v73, v73
	v_add_f32_e32 v15, v15, v70
	v_exp_f32_e32 v74, v74
	v_add_f32_e32 v177, v177, v71
	v_exp_f32_e32 v75, v75
	v_cvt_pk_bf16_f32 v217, v70, v71
	s_waitcnt lgkmcnt(11)
	v_mfma_f32_32x32x16_bf16 v[48:63], v[128:131], v[96:99], v[48:63]
	v_exp_f32_e32 v76, v76
	v_add_f32_e32 v15, v15, v72
	v_exp_f32_e32 v77, v77
	v_add_f32_e32 v177, v177, v73
	v_exp_f32_e32 v78, v78
	v_cvt_pk_bf16_f32 v218, v72, v73
	s_waitcnt lgkmcnt(10)
	v_mfma_f32_32x32x16_bf16 v[48:63], v[132:135], v[100:103], v[48:63]
	v_exp_f32_e32 v79, v79
	v_add_f32_e32 v15, v15, v74
	v_add_f32_e32 v177, v177, v75
	v_cvt_pk_bf16_f32 v219, v74, v75
	v_add_f32_e32 v15, v15, v76
	v_add_f32_e32 v177, v177, v77
	s_waitcnt lgkmcnt(9)
	v_mfma_f32_32x32x16_bf16 v[48:63], v[136:139], v[104:107], v[48:63]
	v_cvt_pk_bf16_f32 v220, v76, v77
	v_add_f32_e32 v15, v15, v78
	v_add_f32_e32 v177, v177, v79
	v_cvt_pk_bf16_f32 v221, v78, v79
	v_add_f32_e32 v15, v15, v177
	v_add_f32_e32 v170, v170, v15
	s_waitcnt lgkmcnt(0)
	v_mfma_f32_32x32x16_bf16 v[16:31], v[214:217], v[140:143], v[16:31]
	ds_read2_b64 v[140:143], v14 offset0:24 offset1:26
	v_mfma_f32_32x32x16_bf16 v[32:47], v[214:217], v[144:147], v[32:47]
	ds_read2_b64 v[144:147], v176 offset0:56 offset1:58
	v_mfma_f32_32x32x16_bf16 v[16:31], v[218:221], v[180:183], v[16:31]
	ds_read2_b64 v[180:183], v14 offset0:28 offset1:30
	v_mfma_f32_32x32x16_bf16 v[32:47], v[218:221], v[184:187], v[32:47]
	ds_read2_b64 v[184:187], v176 offset0:60 offset1:62
	s_nop 3
	v_max3_f32 v15, v48, v49, v50
	v_max3_f32 v177, v51, v52, v53
	v_max3_f32 v15, v15, v54, v55
	v_max3_f32 v177, v177, v56, v57
	v_max3_f32 v15, v15, v58, v59
	v_max3_f32 v177, v177, v60, v61
	v_max3_f32 v15, v15, v62, v63
	v_max_f32_e32 v15, v15, v177
	v_cmp_gt_f32_e32 vcc, v15, v197
	s_cbranch_vccz .Lm3_ok4
	v_mov_b32_e32 v177, v15
	v_mov_b32_e32 v178, v15
	s_nop 1
	v_permlane32_swap_b32_e32 v177, v178
	v_max3_f32 v15, v15, v177, v178
	v_max_f32_e32 v15, v171, v15
	v_sub_f32_e32 v177, v171, v15
	v_exp_f32_e32 v177, v177
	v_sub_f32_e32 v198, v198, v15
	s_and_saveexec_b64 s[20:21], s[40:41]
	ds_write_b32 v149, v177
	s_or_b64 exec, exec, s[20:21]
	v_mul_f32_e32 v170, v170, v177
	v_add_u32_e32 v178, s25, v148
	s_waitcnt lgkmcnt(0)
	ds_read_b128 v[188:191], v178
	ds_read_b128 v[192:195], v178 offset:32
	ds_read_b128 v[222:225], v178 offset:64
	ds_read_b128 v[236:239], v178 offset:96
	v_sub_f32_e32 v48, v48, v15
	v_sub_f32_e32 v49, v49, v15
	v_sub_f32_e32 v50, v50, v15
	v_sub_f32_e32 v51, v51, v15
	v_sub_f32_e32 v52, v52, v15
	v_sub_f32_e32 v53, v53, v15
	v_sub_f32_e32 v54, v54, v15
	v_sub_f32_e32 v55, v55, v15
	v_sub_f32_e32 v56, v56, v15
	v_sub_f32_e32 v57, v57, v15
	v_sub_f32_e32 v58, v58, v15
	v_sub_f32_e32 v59, v59, v15
	v_sub_f32_e32 v60, v60, v15
	v_sub_f32_e32 v61, v61, v15
	v_sub_f32_e32 v62, v62, v15
	v_sub_f32_e32 v63, v63, v15
	v_mov_b32_e32 v199, v198
	v_mov_b32_e32 v200, v198
	v_mov_b32_e32 v201, v198
	v_mov_b32_e32 v202, v198
	v_mov_b32_e32 v203, v198
	v_mov_b32_e32 v204, v198
	v_mov_b32_e32 v205, v198
	v_mov_b32_e32 v206, v198
	v_mov_b32_e32 v207, v198
	v_mov_b32_e32 v208, v198
	v_mov_b32_e32 v209, v198
	v_mov_b32_e32 v210, v198
	v_mov_b32_e32 v211, v198
	v_mov_b32_e32 v212, v198
	v_mov_b32_e32 v213, v198
	v_mov_b32_e32 v171, 0
	v_mov_b32_e32 v197, 0x41000000
	s_nop 11
	s_nop 3
	s_waitcnt lgkmcnt(0)
	v_pk_mul_f32 v[16:17], v[16:17], v[188:189]
	v_pk_mul_f32 v[32:33], v[32:33], v[188:189]
	v_pk_mul_f32 v[18:19], v[18:19], v[190:191]
	v_pk_mul_f32 v[34:35], v[34:35], v[190:191]
	v_pk_mul_f32 v[20:21], v[20:21], v[192:193]
	v_pk_mul_f32 v[36:37], v[36:37], v[192:193]
	v_pk_mul_f32 v[22:23], v[22:23], v[194:195]
	v_pk_mul_f32 v[38:39], v[38:39], v[194:195]
	v_pk_mul_f32 v[24:25], v[24:25], v[222:223]
	v_pk_mul_f32 v[40:41], v[40:41], v[222:223]
	v_pk_mul_f32 v[26:27], v[26:27], v[224:225]
	v_pk_mul_f32 v[42:43], v[42:43], v[224:225]
	v_pk_mul_f32 v[28:29], v[28:29], v[236:237]
	v_pk_mul_f32 v[44:45], v[44:45], v[236:237]
	v_pk_mul_f32 v[30:31], v[30:31], v[238:239]
	v_pk_mul_f32 v[46:47], v[46:47], v[238:239]
; #define LAS __attribute__((address_space(3)))
; #define MFMA32(a, b, c) __builtin_amdgcn_mfma_f32_32x32x16_bf16((a), (b), (c), 0, 0, 0)
; #define SM_LOAD(js) do { kreg0 = *(const u32x4*)(kg + (long)(js) * 128 * ldk); kreg1 = *(const u32x4*)(kg + ((long)(js) * 128 + 64) * ldk); vreg0 = *(const u32x4*)(vg + (js) * 128); vreg1 = *(const u32x4*)(vg + (js) * 128 + 64); \
;         k2reg = *(const u32x4*)(k2g + (long)(js) * 128 * 32); } while (0)
; template <bool MASK> __device__ __forceinline__ void sm_iter(int var, SmState& st, const bf16x8 (&qr)[6], const LAS unsigned char* kb, const LAS unsigned char* vb, LAS float* wsf, int kv0, int qpos, int q32, int hi) {
;     ...
;     for (int d0 = 0; d0 < ND; ++d0) { kf[2 * d0] = *(const LAS bf16x8*)(kb + d0 * 32); kf[2 * d0 + 1] = *(const LAS bf16x8*)(kb + 32 * KP + d0 * 32); }
;     __builtin_amdgcn_sched_barrier(0);
; #pragma unroll
;     for (int d0 = 0; d0 < ND; ++d0) { p0 = MFMA32(kf[2 * d0], qr[d0], p0); p1 = MFMA32(kf[2 * d0 + 1], qr[d0], p1); }
; #pragma unroll
;     for (int j = 0; j < 4; ++j) { vlo[2 * j] = *(const LAS s16x4*)(vb + j * 32); vhh[2 * j] = *(const LAS s16x4*)(vb + j * 32 + 16);
;         vlo[2 * j + 1] = *(const LAS s16x4*)(vb + 32 * VP + j * 32); vhh[2 * j + 1] = *(const LAS s16x4*)(vb + 32 * VP + j * 32 + 16); }
;     __builtin_amdgcn_sched_barrier(0);
;     if (var != 1) sm_tile<MASK>(p0, p1, st.mrun, st.lrun, st.o0, st.o1, wsf, kv0, qpos, q32, hi);
; __device__ __forceinline__ void attn_unit_sm(int b, int h, int qb, const bf16_t* __restrict__ Q, const bf16_t* __restrict__ K, const bf16_t* __restrict__ K2, const bf16_t* __restrict__ Vt, bf16_t* __restrict__ O, const float* __restrict__ cs, LAS unsigned char* lds, int var) {
;     ...
;     for (; it < ns - 2; ++it) {
;         const int cur = it & 1;
;         if (var != 2) SM_LOAD(it + 1);
; #pragma unroll
;         for (int sub = 0; sub < 2; ++sub)
;             sm_iter<false>(var, st, qr, lds + OFF_K + cur * KBUF + (sub * 64 + q32) * KP + hi * 16, lds + OFF_V + cur * VBUF + q32 * VP + sub * 128 + hi * 8, wsf, (2 * it + sub) * 64, qpos, q32, hi);
;         if (var != 2) SM_STORE(cur ^ 1);
;         __syncthreads();
.Lm3_ok4:
	s_add_i32 s19, s19, 1
	s_and_b32 s43, s19, 1
	s_mul_i32 s20, s43, 0x6800
	v_add_u32_e32 v1, s20, v175
	v_lshl_add_u64 v[162:163], v[162:163], 0, s[94:95]
	v_lshl_add_u64 v[164:165], v[164:165], 0, s[96:97]
	v_lshl_add_u64 v[166:167], v[166:167], 0, s[38:39]
	s_cmp_eq_u32 s18, s19
	s_waitcnt lgkmcnt(0)
	s_barrier
	s_cbranch_scc1 .Lm3_drain
	ds_read_b128 v[116:119], v1 offset:0
	ds_read_b128 v[120:123], v1 offset:32
	ds_read_b128 v[124:127], v1 offset:64
	ds_read_b128 v[128:131], v1 offset:96
	ds_read_b128 v[132:135], v1 offset:128
	ds_read_b128 v[136:139], v1 offset:160
	v_lshl_add_u64 v[2:3], s[22:23], 0, v[166:167]
	v_add_co_u32_e32 v4, vcc, 0x104a0000, v2
	v_lshl_add_u64 v[10:11], s[22:23], 0, v[162:163]
	s_nop 0
	v_addc_co_u32_e32 v5, vcc, 0, v3, vcc
	v_add_co_u32_e32 v2, vcc, 0x104c0000, v2
	s_and_b32 s43, s19, 1
	s_nop 0
	v_addc_co_u32_e32 v3, vcc, 0, v3, vcc
	v_add_co_u32_e32 v14, vcc, 0x12460000, v10
	global_load_dwordx4 v[6:9], v[4:5], off
	s_nop 0
	global_load_dwordx4 v[2:5], v[2:3], off
	v_addc_co_u32_e32 v15, vcc, 0, v11, vcc
	global_load_dwordx4 v[10:13], v[14:15], off offset:256
	global_load_dwordx4 v[108:111], v[14:15], off offset:384
	v_lshl_add_u64 v[14:15], s[22:23], 0, v[164:165]
	global_load_dwordx4 v[112:115], v[14:15], off
	s_mul_i32 s20, s43, 0x6800
	v_add_u32_e32 v1, s20, v175
	s_mul_i32 s20, s43, 0x4200
	v_add_u32_e32 v15, s20, v174
	v_add_u32_e32 v14, 0xd000, v15
	v_add_u32_e32 v176, 0xf000, v15
	v_exp_f32_e32 v48, v48
	v_exp_f32_e32 v49, v49
	v_exp_f32_e32 v50, v50
	v_add_f32_e32 v15, v48, v49
	v_exp_f32_e32 v51, v51
	v_cvt_pk_bf16_f32 v214, v48, v49
	v_exp_f32_e32 v52, v52
	v_add_f32_e32 v177, v50, v51
	v_exp_f32_e32 v53, v53
	v_cvt_pk_bf16_f32 v215, v50, v51
	v_exp_f32_e32 v54, v54
	v_add_f32_e32 v15, v15, v52
	v_exp_f32_e32 v55, v55
	v_add_f32_e32 v177, v177, v53
	v_exp_f32_e32 v56, v56
	v_cvt_pk_bf16_f32 v216, v52, v53
	v_exp_f32_e32 v57, v57
	v_add_f32_e32 v15, v15, v54
	v_exp_f32_e32 v58, v58
	v_add_f32_e32 v177, v177, v55
	v_exp_f32_e32 v59, v59
	v_cvt_pk_bf16_f32 v217, v54, v55
	v_exp_f32_e32 v60, v60
	v_add_f32_e32 v15, v15, v56
	v_exp_f32_e32 v61, v61
	v_add_f32_e32 v177, v177, v57
	v_exp_f32_e32 v62, v62
	v_cvt_pk_bf16_f32 v218, v56, v57
	s_waitcnt lgkmcnt(5)
	v_mfma_f32_32x32x16_bf16 v[64:79], v[116:119], v[84:87], v[198:213]
	v_exp_f32_e32 v63, v63
	v_add_f32_e32 v15, v15, v58
	s_waitcnt lgkmcnt(4)
	v_mfma_f32_32x32x16_bf16 v[64:79], v[120:123], v[88:91], v[64:79]
	v_add_f32_e32 v177, v177, v59
	v_cvt_pk_bf16_f32 v219, v58, v59
	s_waitcnt lgkmcnt(3)
	v_mfma_f32_32x32x16_bf16 v[64:79], v[124:127], v[92:95], v[64:79]
	v_add_f32_e32 v15, v15, v60
	v_add_f32_e32 v177, v177, v61
	s_waitcnt lgkmcnt(2)
	v_mfma_f32_32x32x16_bf16 v[64:79], v[128:131], v[96:99], v[64:79]
	v_cvt_pk_bf16_f32 v220, v60, v61
	v_add_f32_e32 v15, v15, v62
	s_waitcnt lgkmcnt(1)
	v_mfma_f32_32x32x16_bf16 v[64:79], v[132:135], v[100:103], v[64:79]
	v_add_f32_e32 v177, v177, v63
	v_cvt_pk_bf16_f32 v221, v62, v63
	s_waitcnt lgkmcnt(0)
	v_mfma_f32_32x32x16_bf16 v[64:79], v[136:139], v[104:107], v[64:79]
	v_add_f32_e32 v15, v15, v177
	v_add_f32_e32 v170, v170, v15
	s_waitcnt lgkmcnt(0)
	ds_read_b128 v[116:119], v1 offset:6656
	ds_read_b128 v[120:123], v1 offset:6688
	ds_read_b128 v[124:127], v1 offset:6720
	ds_read_b128 v[128:131], v1 offset:6752
	ds_read_b128 v[132:135], v1 offset:6784
	ds_read_b128 v[136:139], v1 offset:6816
	v_mfma_f32_32x32x16_bf16 v[16:31], v[214:217], v[140:143], v[16:31]
	ds_read2_b64 v[140:143], v14 offset0:0 offset1:2
	v_mfma_f32_32x32x16_bf16 v[32:47], v[214:217], v[144:147], v[32:47]
	ds_read2_b64 v[144:147], v176 offset0:32 offset1:34
	v_mfma_f32_32x32x16_bf16 v[16:31], v[218:221], v[180:183], v[16:31]
	ds_read2_b64 v[180:183], v14 offset0:4 offset1:6
	v_mfma_f32_32x32x16_bf16 v[32:47], v[218:221], v[184:187], v[32:47]
	ds_read2_b64 v[184:187], v176 offset0:36 offset1:38
	v_max3_f32 v15, v64, v65, v66
	v_max3_f32 v177, v67, v68, v69
	v_max3_f32 v15, v15, v70, v71
	v_max3_f32 v177, v177, v72, v73
	v_max3_f32 v15, v15, v74, v75
	v_max3_f32 v177, v177, v76, v77
	v_max3_f32 v15, v15, v78, v79
	v_max_f32_e32 v15, v15, v177
	v_cmp_gt_f32_e32 vcc, v15, v197
	s_cbranch_vccz .Lm3_ok5
	v_mov_b32_e32 v177, v15
	v_mov_b32_e32 v178, v15
	s_nop 1
	v_permlane32_swap_b32_e32 v177, v178
	v_max3_f32 v15, v15, v177, v178
	v_max_f32_e32 v15, v171, v15
	v_sub_f32_e32 v177, v171, v15
	v_exp_f32_e32 v177, v177
	v_sub_f32_e32 v198, v198, v15
	s_and_saveexec_b64 s[20:21], s[40:41]
	ds_write_b32 v149, v177
	s_or_b64 exec, exec, s[20:21]
	v_mul_f32_e32 v170, v170, v177
	v_add_u32_e32 v178, s25, v148
	s_waitcnt lgkmcnt(0)
	ds_read_b128 v[188:191], v178
	ds_read_b128 v[192:195], v178 offset:32
	ds_read_b128 v[222:225], v178 offset:64
	ds_read_b128 v[236:239], v178 offset:96
	v_sub_f32_e32 v64, v64, v15
	v_sub_f32_e32 v65, v65, v15
	v_sub_f32_e32 v66, v66, v15
	v_sub_f32_e32 v67, v67, v15
	v_sub_f32_e32 v68, v68, v15
	v_sub_f32_e32 v69, v69, v15
	v_sub_f32_e32 v70, v70, v15
	v_sub_f32_e32 v71, v71, v15
	v_sub_f32_e32 v72, v72, v15
	v_sub_f32_e32 v73, v73, v15
	v_sub_f32_e32 v74, v74, v15
	v_sub_f32_e32 v75, v75, v15
	v_sub_f32_e32 v76, v76, v15
	v_sub_f32_e32 v77, v77, v15
	v_sub_f32_e32 v78, v78, v15
	v_sub_f32_e32 v79, v79, v15
	v_mov_b32_e32 v199, v198
	v_mov_b32_e32 v200, v198
	v_mov_b32_e32 v201, v198
	v_mov_b32_e32 v202, v198
	v_mov_b32_e32 v203, v198
	v_mov_b32_e32 v204, v198
	v_mov_b32_e32 v205, v198
	v_mov_b32_e32 v206, v198
	v_mov_b32_e32 v207, v198
	v_mov_b32_e32 v208, v198
	v_mov_b32_e32 v209, v198
	v_mov_b32_e32 v210, v198
	v_mov_b32_e32 v211, v198
	v_mov_b32_e32 v212, v198
	v_mov_b32_e32 v213, v198
	v_mov_b32_e32 v171, 0
	v_mov_b32_e32 v197, 0x41000000
	s_nop 11
	s_nop 3
	s_waitcnt lgkmcnt(0)
	v_pk_mul_f32 v[16:17], v[16:17], v[188:189]
	v_pk_mul_f32 v[32:33], v[32:33], v[188:189]
	v_pk_mul_f32 v[18:19], v[18:19], v[190:191]
	v_pk_mul_f32 v[34:35], v[34:35], v[190:191]
	v_pk_mul_f32 v[20:21], v[20:21], v[192:193]
	v_pk_mul_f32 v[36:37], v[36:37], v[192:193]
	v_pk_mul_f32 v[22:23], v[22:23], v[194:195]
	v_pk_mul_f32 v[38:39], v[38:39], v[194:195]
	v_pk_mul_f32 v[24:25], v[24:25], v[222:223]
	v_pk_mul_f32 v[40:41], v[40:41], v[222:223]
	v_pk_mul_f32 v[26:27], v[26:27], v[224:225]
	v_pk_mul_f32 v[42:43], v[42:43], v[224:225]
	v_pk_mul_f32 v[28:29], v[28:29], v[236:237]
	v_pk_mul_f32 v[44:45], v[44:45], v[236:237]
	v_pk_mul_f32 v[30:31], v[30:31], v[238:239]
	v_pk_mul_f32 v[46:47], v[46:47], v[238:239]
